# flattened MoBA gate loop skips the upper 8 past blocks when the query block index is <= 8
# baseline (speedup 1.0000x reference)
; #define LAS __attribute__((address_space(3)))
; __device__ __forceinline__ void moba_select(LAS unsigned char* lds, const bf16_t* Qp, int ld, int rowbase, int ob, const float* kmean_bh) {
;     ...
;       for (int c = 0; c < 16; ++c) {
;           const u32x4 qv = *(const u32x4*)(qrow + c * 8);
;           float qfv[8]; qfv[0] = bflo(qv.x); qfv[1] = bfhi(qv.x); qfv[2] = bflo(qv.y); qfv[3] = bfhi(qv.y); qfv[4] = bflo(qv.z); qfv[5] = bfhi(qv.z); qfv[6] = bflo(qv.w); qfv[7] = bfhi(qv.w);
; #pragma unroll
;           for (int jj = 0; jj < 8; ++jj) { const int j = 2 * jj + par;
;               if (j < ob) { const LAS float* km = km_s + j * 128 + c * 8; const f32x4 ka = *(const LAS f32x4*)km, kb = *(const LAS f32x4*)(km + 4);
;                   acc[jj] += qfv[0] * ka[0] + qfv[1] * ka[1] + qfv[2] * ka[2] + qfv[3] * ka[3] + qfv[4] * kb[0] + qfv[5] * kb[1] + qfv[6] * kb[2] + qfv[7] * kb[3]; } }
;       }
.LBB0_891:
	v_add_u32_e32 v0, s18, v182
	s_waitcnt vmcnt(0)
	v_lshlrev_b32_e32 v2, 16, v230
	v_and_b32_e32 v3, 0xffff0000, v230
	v_and_b32_e32 v5, 0xffff0000, v231
	v_lshlrev_b32_e32 v4, 16, v231
	v_and_b32_e32 v7, 0xffff0000, v232
	v_lshlrev_b32_e32 v6, 16, v232
	v_and_b32_e32 v35, 0xffff0000, v233
	v_lshlrev_b32_e32 v34, 16, v233
	v_lshl_add_u64 v[32:33], v[32:33], 0, 16
	global_load_dwordx4 v[230:233], v[32:33], off
	v_add_u32_e32 v36, 0x1b000, v0
	ds_read_b128 v[44:47], v36
	ds_read_b128 v[48:51], v36 offset:16
	ds_read_b128 v[52:55], v36 offset:1024
	ds_read_b128 v[56:59], v36 offset:1040
	ds_read_b128 v[60:63], v36 offset:2048
	ds_read_b128 v[64:67], v36 offset:2064
	ds_read_b128 v[68:71], v36 offset:3072
	ds_read_b128 v[72:75], v36 offset:3088
	s_waitcnt lgkmcnt(7)
	v_pk_mul_f32 v[44:45], v[44:45], v[2:3]
	v_pk_mul_f32 v[46:47], v[46:47], v[4:5]
	v_add_f32_e32 v37, v44, v45
	v_add_f32_e32 v37, v46, v37
	s_waitcnt lgkmcnt(6)
	v_pk_mul_f32 v[48:49], v[48:49], v[6:7]
	v_add_f32_e32 v37, v47, v37
	v_add_f32_e32 v37, v48, v37
	v_pk_mul_f32 v[50:51], v[50:51], v[34:35]
	v_add_f32_e32 v37, v49, v37
	v_add_f32_e32 v37, v50, v37
	v_add_f32_e32 v37, v51, v37
	v_add_f32_e32 v24, v24, v37
	s_waitcnt lgkmcnt(5)
	v_pk_mul_f32 v[52:53], v[52:53], v[2:3]
	v_pk_mul_f32 v[54:55], v[54:55], v[4:5]
	v_add_f32_e32 v37, v52, v53
	v_add_f32_e32 v37, v54, v37
	s_waitcnt lgkmcnt(4)
	v_pk_mul_f32 v[56:57], v[56:57], v[6:7]
	v_add_f32_e32 v37, v55, v37
	v_add_f32_e32 v37, v56, v37
	v_pk_mul_f32 v[58:59], v[58:59], v[34:35]
	v_add_f32_e32 v37, v57, v37
	v_add_f32_e32 v37, v58, v37
	v_add_f32_e32 v37, v59, v37
	v_add_f32_e32 v25, v25, v37
	s_waitcnt lgkmcnt(3)
	v_pk_mul_f32 v[60:61], v[60:61], v[2:3]
	v_pk_mul_f32 v[62:63], v[62:63], v[4:5]
	v_add_f32_e32 v37, v60, v61
	v_add_f32_e32 v37, v62, v37
	s_waitcnt lgkmcnt(2)
	v_pk_mul_f32 v[64:65], v[64:65], v[6:7]
	v_add_f32_e32 v37, v63, v37
	v_add_f32_e32 v37, v64, v37
	v_pk_mul_f32 v[66:67], v[66:67], v[34:35]
	v_add_f32_e32 v37, v65, v37
	v_add_f32_e32 v37, v66, v37
	v_add_f32_e32 v37, v67, v37
	v_add_f32_e32 v26, v26, v37
	s_waitcnt lgkmcnt(1)
	v_pk_mul_f32 v[68:69], v[68:69], v[2:3]
	v_pk_mul_f32 v[70:71], v[70:71], v[4:5]
	v_add_f32_e32 v37, v68, v69
	v_add_f32_e32 v37, v70, v37
	s_waitcnt lgkmcnt(0)
	v_pk_mul_f32 v[72:73], v[72:73], v[6:7]
	v_add_f32_e32 v37, v71, v37
	v_add_f32_e32 v37, v72, v37
	v_pk_mul_f32 v[74:75], v[74:75], v[34:35]
	v_add_f32_e32 v37, v73, v37
	v_add_f32_e32 v37, v74, v37
	v_add_f32_e32 v37, v75, v37
	v_add_f32_e32 v27, v27, v37
	s_cmpk_lt_u32 s35, 9
	s_cbranch_scc1 .Lgate_half_done
	ds_read_b128 v[44:47], v36 offset:4096
	ds_read_b128 v[48:51], v36 offset:4112
	ds_read_b128 v[52:55], v36 offset:5120
	ds_read_b128 v[56:59], v36 offset:5136
	ds_read_b128 v[60:63], v36 offset:6144
	ds_read_b128 v[64:67], v36 offset:6160
	ds_read_b128 v[68:71], v36 offset:7168
	ds_read_b128 v[72:75], v36 offset:7184
	s_waitcnt lgkmcnt(7)
	v_pk_mul_f32 v[44:45], v[44:45], v[2:3]
	v_pk_mul_f32 v[46:47], v[46:47], v[4:5]
	v_add_f32_e32 v37, v44, v45
	v_add_f32_e32 v37, v46, v37
	s_waitcnt lgkmcnt(6)
	v_pk_mul_f32 v[48:49], v[48:49], v[6:7]
	v_add_f32_e32 v37, v47, v37
	v_add_f32_e32 v37, v48, v37
	v_pk_mul_f32 v[50:51], v[50:51], v[34:35]
	v_add_f32_e32 v37, v49, v37
	v_add_f32_e32 v37, v50, v37
	v_add_f32_e32 v37, v51, v37
	v_add_f32_e32 v28, v28, v37
	s_waitcnt lgkmcnt(5)
	v_pk_mul_f32 v[52:53], v[52:53], v[2:3]
	v_pk_mul_f32 v[54:55], v[54:55], v[4:5]
	v_add_f32_e32 v37, v52, v53
	v_add_f32_e32 v37, v54, v37
	s_waitcnt lgkmcnt(4)
	v_pk_mul_f32 v[56:57], v[56:57], v[6:7]
	v_add_f32_e32 v37, v55, v37
	v_add_f32_e32 v37, v56, v37
	v_pk_mul_f32 v[58:59], v[58:59], v[34:35]
	v_add_f32_e32 v37, v57, v37
	v_add_f32_e32 v37, v58, v37
	v_add_f32_e32 v37, v59, v37
	v_add_f32_e32 v29, v29, v37
	s_waitcnt lgkmcnt(3)
	v_pk_mul_f32 v[60:61], v[60:61], v[2:3]
	v_pk_mul_f32 v[62:63], v[62:63], v[4:5]
	v_add_f32_e32 v37, v60, v61
	v_add_f32_e32 v37, v62, v37
	s_waitcnt lgkmcnt(2)
	v_pk_mul_f32 v[64:65], v[64:65], v[6:7]
	v_add_f32_e32 v37, v63, v37
	v_add_f32_e32 v37, v64, v37
	v_pk_mul_f32 v[66:67], v[66:67], v[34:35]
	v_add_f32_e32 v37, v65, v37
	v_add_f32_e32 v37, v66, v37
	v_add_f32_e32 v37, v67, v37
	v_add_f32_e32 v30, v30, v37
	s_waitcnt lgkmcnt(1)
	v_pk_mul_f32 v[68:69], v[68:69], v[2:3]
	v_pk_mul_f32 v[70:71], v[70:71], v[4:5]
	v_add_f32_e32 v37, v68, v69
	v_add_f32_e32 v37, v70, v37
	s_waitcnt lgkmcnt(0)
	v_pk_mul_f32 v[72:73], v[72:73], v[6:7]
	v_add_f32_e32 v37, v71, v37
	v_add_f32_e32 v37, v72, v37
	v_pk_mul_f32 v[74:75], v[74:75], v[34:35]
	v_add_f32_e32 v37, v73, v37
	v_add_f32_e32 v37, v74, v37
	v_add_f32_e32 v37, v75, v37
	v_add_f32_e32 v31, v31, v37
.Lgate_half_done:
	s_add_i32 s18, s18, 32
	s_cmpk_eq_i32 s18, 0x200
	s_cbranch_scc0 .LBB0_891
